# phase 10 row loop runs from the highest row down, so the latency-bound sample-row iteration of the first 64 workgroups overlaps the streaming of the others instead of forming the tail
# baseline (speedup 1.0000x reference)
.LBB0_1486:
	s_lshl_b32 s2, s94, 3
	v_ashrrev_i32_e32 v16, 6, v156
	v_add_u32_e32 v81, s2, v16
	s_movk_i32 s24, 0x4200
	v_cmp_gt_i32_e32 vcc, s24, v81
	s_and_saveexec_b64 s[8:9], vcc
	s_cbranch_execz .LBB0_1525
	s_load_dwordx4 s[4:7], s[0:1], 0xd0
	s_load_dwordx2 s[14:15], s[0:1], 0xe0
	v_lshlrev_b32_e32 v0, 2, v156
	v_and_b32_e32 v80, 0xfc, v0
	v_lshlrev_b32_e32 v82, 2, v80
	s_waitcnt lgkmcnt(0)
	global_load_dwordx4 v[0:3], v82, s[4:5]
	global_load_dwordx4 v[4:7], v82, s[4:5] offset:1024
	global_load_dwordx4 v[8:11], v82, s[4:5] offset:2048
	global_load_dwordx4 v[12:15], v82, s[4:5] offset:3072
	s_add_u32 s4, s14, 0xddf0000
	s_addc_u32 s5, s15, 0
	s_add_u32 s10, s14, 0x9bf0000
	s_addc_u32 s11, s15, 0
	s_lshl_b32 s25, s34, 3
	s_lshl_b32 s12, s34, 4
	s_sub_i32 s12, 0, s12
	s_add_u32 s14, s14, 0x9bf0800
	s_addc_u32 s15, s15, 0
	v_ashrrev_i32_e32 v17, 31, v16
	s_ashr_i32 s3, s2, 31
	v_lshl_add_u64 v[16:17], v[16:17], 0, s[2:3]
	v_mov_b32_e32 v83, 0
	v_lshlrev_b64 v[94:95], 12, v[16:17]
	v_and_b32_e32 v16, 63, v156
	s_ashr_i32 s13, s12, 31
	v_lshl_add_u64 v[84:85], s[4:5], 0, v[82:83]
	v_or_b32_e32 v86, 0x100, v80
	v_or_b32_e32 v88, 0x200, v80
	v_or_b32_e32 v90, 0x300, v80
	v_lshl_add_u64 v[92:93], s[6:7], 0, v[82:83]
	v_lshl_or_b32 v94, v16, 4, v94
	s_lshl_b64 s[16:17], s[12:13], 12
	s_mov_b64 s[18:19], 0
	s_movk_i32 s13, 0x3fff
	s_mov_b32 s26, 0x800000
	v_mov_b32_e32 v87, 0x358637bd
	s_movk_i32 s27, 0x41ff
	v_cmp_gt_i32_e32 vcc, 0x200, v81
	v_mov_b32_e32 v96, 3
	s_nop 1
	v_cndmask_b32_e64 v96, v96, 4, vcc
	v_lshlrev_b32_e32 v97, 12, v96
	v_add_u32_e32 v81, v81, v97
	v_lshlrev_b32_e32 v97, 24, v96
	v_add_co_u32_e32 v94, vcc, v94, v97
	v_addc_co_u32_e32 v95, vcc, 0, v95, vcc
	s_branch .LBB0_1489
.LBB0_1488:
	s_or_b64 exec, exec, s[2:3]
	v_add_u32_e32 v81, s12, v81
	v_cmp_gt_i32_e32 vcc, 0, v81
	s_or_b64 s[18:19], vcc, s[18:19]
	v_lshl_add_u64 v[94:95], v[94:95], 0, s[16:17]
	s_andn2_b64 exec, exec, s[18:19]
	s_cbranch_execz .LBB0_1525
